# speedup vs baseline: 1.0055x; 1.0047x over previous
; DEVI unsigned pack2(float a, float b) { f32v2 v = {a, b}; return __builtin_bit_cast(unsigned, __builtin_convertvector(v, bf16v2)); }
; __device__ void conv_rows(const float* __restrict__ src, u16* __restrict__ dst, size_t n4, size_t gtid, size_t gsz) {
;   size_t i = gtid;
;   for (; i + 7 * gsz < n4; i += 8 * gsz) {
;     float4 v[8];
; #pragma unroll
;     for (int u = 0; u < 8; ++u) v[u] = ((const float4*)src)[i + u * gsz];
; #pragma unroll
;     for (int u = 0; u < 8; ++u) { uint2 o; o.x = pack2(v[u].x, v[u].y); o.y = pack2(v[u].z, v[u].w); ((uint2*)dst)[i + u * gsz] = o; }
;   }
.LBB0_76:
	global_load_dwordx4 v[10:13], v[6:7], off nt
	v_lshl_add_u64 v[18:19], v[6:7], 0, s[10:11]
	global_load_dwordx4 v[14:17], v[18:19], off nt
	v_lshl_add_u64 v[22:23], v[18:19], 0, s[10:11]
	global_load_dwordx4 v[18:21], v[22:23], off nt
	v_lshl_add_u64 v[26:27], v[22:23], 0, s[10:11]
	global_load_dwordx4 v[22:25], v[26:27], off nt
	v_lshl_add_u64 v[30:31], v[26:27], 0, s[10:11]
	global_load_dwordx4 v[26:29], v[30:31], off nt
	v_lshl_add_u64 v[34:35], v[30:31], 0, s[10:11]
	global_load_dwordx4 v[30:33], v[34:35], off nt
	v_lshl_add_u64 v[38:39], v[34:35], 0, s[10:11]
	global_load_dwordx4 v[34:37], v[38:39], off nt
	v_lshl_add_u64 v[38:39], v[38:39], 0, s[10:11]
	global_load_dwordx4 v[38:41], v[38:39], off nt
	v_lshl_add_u64 v[42:43], v[8:9], 0, s[8:9]
	v_lshl_add_u64 v[4:5], v[4:5], 0, s[8:9]
	v_lshl_add_u64 v[44:45], v[42:43], 0, s[8:9]
	v_lshl_add_u64 v[46:47], s[4:5], 0, v[4:5]
	v_lshl_add_u64 v[48:49], v[44:45], 0, s[8:9]
	v_cmp_lt_u64_e32 vcc, s[66:67], v[46:47]
	v_lshl_add_u64 v[46:47], v[48:49], 0, s[8:9]
	v_lshl_add_u64 v[50:51], v[46:47], 0, s[8:9]
	v_lshl_add_u64 v[52:53], v[50:51], 0, s[8:9]
	s_or_b64 s[62:63], vcc, s[62:63]
	v_lshl_add_u64 v[54:55], v[52:53], 0, s[8:9]
	v_lshl_add_u64 v[6:7], v[6:7], 0, s[60:61]
	s_waitcnt vmcnt(7)
	v_cvt_pk_bf16_f32 v10, v10, v11
	v_cvt_pk_bf16_f32 v11, v12, v13
	global_store_dwordx2 v[8:9], v[10:11], off
	s_waitcnt vmcnt(7)
	v_cvt_pk_bf16_f32 v10, v14, v15
	v_cvt_pk_bf16_f32 v11, v16, v17
	global_store_dwordx2 v[42:43], v[10:11], off
	s_waitcnt vmcnt(7)
	v_cvt_pk_bf16_f32 v10, v18, v19
	v_cvt_pk_bf16_f32 v11, v20, v21
	global_store_dwordx2 v[44:45], v[10:11], off
	s_waitcnt vmcnt(7)
	v_cvt_pk_bf16_f32 v10, v22, v23
	v_cvt_pk_bf16_f32 v11, v24, v25
	global_store_dwordx2 v[48:49], v[10:11], off
	s_waitcnt vmcnt(7)
	v_cvt_pk_bf16_f32 v10, v26, v27
	v_cvt_pk_bf16_f32 v11, v28, v29
	global_store_dwordx2 v[46:47], v[10:11], off
	s_waitcnt vmcnt(7)
	v_cvt_pk_bf16_f32 v10, v30, v31
	v_cvt_pk_bf16_f32 v11, v32, v33
	global_store_dwordx2 v[50:51], v[10:11], off
	s_waitcnt vmcnt(7)
	v_cvt_pk_bf16_f32 v10, v34, v35
	v_cvt_pk_bf16_f32 v11, v36, v37
	v_lshl_add_u64 v[8:9], v[8:9], 0, s[64:65]
	global_store_dwordx2 v[52:53], v[10:11], off
	s_waitcnt vmcnt(7)
	v_cvt_pk_bf16_f32 v10, v38, v39
	v_cvt_pk_bf16_f32 v11, v40, v41
	global_store_dwordx2 v[54:55], v[10:11], off
	s_andn2_b64 exec, exec, s[62:63]
	s_cbranch_execnz .LBB0_76
	s_or_b64 exec, exec, s[62:63]

; DEVI unsigned pack2(float a, float b) { f32v2 v = {a, b}; return __builtin_bit_cast(unsigned, __builtin_convertvector(v, bf16v2)); }
; __device__ void conv_rows(const float* __restrict__ src, u16* __restrict__ dst, size_t n4, size_t gtid, size_t gsz) {
;     ...
;   for (; i < n4; i += gsz) {
;     float4 v = ((const float4*)src)[i];
;     uint2 o; o.x = pack2(v.x, v.y); o.y = pack2(v.z, v.w);
;     ((uint2*)dst)[i] = o;
;   }
.LBB0_80:
	global_load_dwordx4 v[10:13], v[6:7], off offset:-8 nt
	v_lshl_add_u64 v[4:5], v[4:5], 0, s[60:61]
	v_cmp_lt_u64_e32 vcc, s[64:65], v[4:5]
	v_lshl_add_u64 v[6:7], v[6:7], 0, s[8:9]
	s_or_b64 s[62:63], vcc, s[62:63]
	s_waitcnt vmcnt(0)
	v_cvt_pk_bf16_f32 v10, v10, v11
	v_cvt_pk_bf16_f32 v11, v12, v13
	global_store_dwordx2 v[8:9], v[10:11], off offset:-4
	v_lshl_add_u64 v[8:9], v[8:9], 0, s[10:11]
	s_andn2_b64 exec, exec, s[62:63]
	s_cbranch_execnz .LBB0_80

; DEVI unsigned pack2(float a, float b) { f32v2 v = {a, b}; return __builtin_bit_cast(unsigned, __builtin_convertvector(v, bf16v2)); }
; __device__ void conv_rows(const float* __restrict__ src, u16* __restrict__ dst, size_t n4, size_t gtid, size_t gsz) {
;     ...
;   for (; i + 7 * gsz < n4; i += 8 * gsz) {
;     float4 v[8];
; #pragma unroll
;     for (int u = 0; u < 8; ++u) v[u] = ((const float4*)src)[i + u * gsz];
; #pragma unroll
;     for (int u = 0; u < 8; ++u) { uint2 o; o.x = pack2(v[u].x, v[u].y); o.y = pack2(v[u].z, v[u].w); ((uint2*)dst)[i + u * gsz] = o; }
;   }
.LBB0_83:
	global_load_dwordx4 v[8:11], v[4:5], off nt
	v_lshl_add_u64 v[16:17], v[4:5], 0, s[10:11]
	global_load_dwordx4 v[12:15], v[16:17], off nt
	v_lshl_add_u64 v[20:21], v[16:17], 0, s[10:11]
	global_load_dwordx4 v[16:19], v[20:21], off nt
	v_lshl_add_u64 v[24:25], v[20:21], 0, s[10:11]
	global_load_dwordx4 v[20:23], v[24:25], off nt
	v_lshl_add_u64 v[28:29], v[24:25], 0, s[10:11]
	global_load_dwordx4 v[24:27], v[28:29], off nt
	v_lshl_add_u64 v[32:33], v[28:29], 0, s[10:11]
	global_load_dwordx4 v[28:31], v[32:33], off nt
	v_lshl_add_u64 v[36:37], v[32:33], 0, s[10:11]
	global_load_dwordx4 v[32:35], v[36:37], off nt
	v_lshl_add_u64 v[36:37], v[36:37], 0, s[10:11]
	global_load_dwordx4 v[36:39], v[36:37], off nt
	v_lshl_add_u64 v[40:41], v[6:7], 0, s[8:9]
	v_lshl_add_u64 v[2:3], v[2:3], 0, s[8:9]
	v_lshl_add_u64 v[42:43], v[40:41], 0, s[8:9]
	v_lshl_add_u64 v[44:45], s[4:5], 0, v[2:3]
	v_lshl_add_u64 v[46:47], v[42:43], 0, s[8:9]
	v_cmp_lt_u64_e32 vcc, s[68:69], v[44:45]
	v_lshl_add_u64 v[44:45], v[46:47], 0, s[8:9]
	v_lshl_add_u64 v[48:49], v[44:45], 0, s[8:9]
	v_lshl_add_u64 v[50:51], v[48:49], 0, s[8:9]
	s_or_b64 s[64:65], vcc, s[64:65]
	v_lshl_add_u64 v[52:53], v[50:51], 0, s[8:9]
	v_lshl_add_u64 v[4:5], v[4:5], 0, s[62:63]
	s_waitcnt vmcnt(7)
	v_cvt_pk_bf16_f32 v8, v8, v9
	v_cvt_pk_bf16_f32 v9, v10, v11
	global_store_dwordx2 v[6:7], v[8:9], off
	s_waitcnt vmcnt(7)
	v_cvt_pk_bf16_f32 v8, v12, v13
	v_cvt_pk_bf16_f32 v9, v14, v15
	global_store_dwordx2 v[40:41], v[8:9], off
	s_waitcnt vmcnt(7)
	v_cvt_pk_bf16_f32 v8, v16, v17
	v_cvt_pk_bf16_f32 v9, v18, v19
	global_store_dwordx2 v[42:43], v[8:9], off
	s_waitcnt vmcnt(7)
	v_cvt_pk_bf16_f32 v8, v20, v21
	v_cvt_pk_bf16_f32 v9, v22, v23
	global_store_dwordx2 v[46:47], v[8:9], off
	s_waitcnt vmcnt(7)
	v_cvt_pk_bf16_f32 v8, v24, v25
	v_cvt_pk_bf16_f32 v9, v26, v27
	global_store_dwordx2 v[44:45], v[8:9], off
	s_waitcnt vmcnt(7)
	v_cvt_pk_bf16_f32 v8, v28, v29
	v_cvt_pk_bf16_f32 v9, v30, v31
	global_store_dwordx2 v[48:49], v[8:9], off
	s_waitcnt vmcnt(7)
	v_cvt_pk_bf16_f32 v8, v32, v33
	v_cvt_pk_bf16_f32 v9, v34, v35
	v_lshl_add_u64 v[6:7], v[6:7], 0, s[66:67]
	global_store_dwordx2 v[50:51], v[8:9], off
	s_waitcnt vmcnt(7)
	v_cvt_pk_bf16_f32 v8, v36, v37
	v_cvt_pk_bf16_f32 v9, v38, v39
	global_store_dwordx2 v[52:53], v[8:9], off
	s_andn2_b64 exec, exec, s[64:65]
	s_cbranch_execnz .LBB0_83
	s_or_b64 exec, exec, s[64:65]

; DEVI unsigned pack2(float a, float b) { f32v2 v = {a, b}; return __builtin_bit_cast(unsigned, __builtin_convertvector(v, bf16v2)); }
; __device__ void conv_rows(const float* __restrict__ src, u16* __restrict__ dst, size_t n4, size_t gtid, size_t gsz) {
;     ...
;   for (; i < n4; i += gsz) {
;     float4 v = ((const float4*)src)[i];
;     uint2 o; o.x = pack2(v.x, v.y); o.y = pack2(v.z, v.w);
;     ((uint2*)dst)[i] = o;
;   }
.LBB0_87:
	global_load_dwordx4 v[8:11], v[4:5], off offset:-8 nt
	v_lshl_add_u64 v[2:3], v[2:3], 0, s[60:61]
	v_cmp_lt_u64_e32 vcc, s[38:39], v[2:3]
	v_lshl_add_u64 v[4:5], v[4:5], 0, s[6:7]
	s_or_b64 s[10:11], vcc, s[10:11]
	s_waitcnt vmcnt(0)
	v_cvt_pk_bf16_f32 v8, v8, v9
	v_cvt_pk_bf16_f32 v9, v10, v11
	global_store_dwordx2 v[6:7], v[8:9], off
	v_lshl_add_u64 v[6:7], v[6:7], 0, s[8:9]
	s_andn2_b64 exec, exec, s[10:11]
	s_cbranch_execnz .LBB0_87

; DEVI unsigned pack2(float a, float b) { f32v2 v = {a, b}; return __builtin_bit_cast(unsigned, __builtin_convertvector(v, bf16v2)); }
; DEVI void lds_barrier() { asm volatile("s_waitcnt lgkmcnt(0)" ::: "memory"); __builtin_amdgcn_s_barrier(); asm volatile("" ::: "memory"); }
; DEVI void tconv_store(const TcPre& R, u16* __restrict__ Wt, int K, int N, int t, float* lds, bool perm) {
;   const int tid = threadIdx.x;
;   const int tnN = N / 128;
;   int tk = t / tnN, tn = t % tnN, k0 = tk * 64, n0 = tn * 128;
;   {
;     float* d = lds + (tid >> 5) * 129 + (tid & 31) * 4;
;     d[0] = R.a[0]; d[1] = R.a[1]; d[2] = R.a[2]; d[3] = R.a[3];
;     d[16 * 129] = R.b[0]; d[16 * 129 + 1] = R.b[1]; d[16 * 129 + 2] = R.b[2]; d[16 * 129 + 3] = R.b[3];
;     d[32 * 129] = R.c[0]; d[32 * 129 + 1] = R.c[1]; d[32 * 129 + 2] = R.c[2]; d[32 * 129 + 3] = R.c[3];
;     d[48 * 129] = R.d[0]; d[48 * 129 + 1] = R.d[1]; d[48 * 129 + 2] = R.d[2]; d[48 * 129 + 3] = R.d[3];
;   }
;   lds_barrier();
;   int n0p = !perm ? n0 : (n0 < DFF ? (n0 / 128) * 256 : ((n0 - DFF) / 128) * 256 + 128);
; #pragma unroll
;   for (int p = 0; p < 2; ++p) {
;     int item = p * 512 + tid, n = item >> 3, kg = item & 7;
;     const float* s = lds + (kg * 8) * 129 + n;
;     uint4 o;
;     o.x = pack2(s[0], s[129]); o.y = pack2(s[2 * 129], s[3 * 129]);
;     o.z = pack2(s[4 * 129], s[5 * 129]); o.w = pack2(s[6 * 129], s[7 * 129]);
;     *(uint4*)(Wt + (size_t)(n0p + n) * K + k0 + kg * 8) = o;
;   }
;   lds_barrier();
; }
; DEVI void tconv(const float* __restrict__ W, u16* __restrict__ Wt, int K, int N, float* lds) {
;   const int ntile = (K / 64) * (N / 128);
;   TcPre R;
;   int t = blockIdx.x;
;   if (t < ntile) tconv_load(W, N, t, R);
;   for (; t < ntile; t += gridDim.x) {
;     TcPre C = R;
;     int nx = t + (int)gridDim.x;
;     tconv_load(W, N, nx < ntile ? nx : t, R);
;     tconv_store(C, Wt, K, N, t, lds, false);
;   }
; }
.LBB0_102:
	s_or_b64 exec, exec, s[4:5]
	s_cmpk_gt_i32 s2, 0x19ff
	s_cbranch_scc1 .LBB0_105
	s_mul_hi_i32 s3, s2, 0x4ec4ec4f
	s_lshr_b32 s4, s3, 31
	s_ashr_i32 s3, s3, 5
	s_add_i32 s3, s3, s4
	s_mul_i32 s4, s3, 0x68
	v_lshrrev_b32_e32 v22, 5, v164
	s_sub_i32 s4, s2, s4
	v_lshl_or_b32 v2, s3, 6, v22
	s_mov_b32 s3, 0xd000
	v_mov_b64_e32 v[0:1], s[42:43]
	s_lshl_b32 s4, s4, 7
	v_mad_i64_i32 v[0:1], s[6:7], v2, s3, v[0:1]
	v_lshlrev_b32_e32 v2, 2, v164
	s_ashr_i32 s5, s4, 31
	v_and_b32_e32 v28, 0x7c, v2
	v_lshl_add_u64 v[0:1], s[4:5], 2, v[0:1]
	v_mov_b32_e32 v17, 0
	v_lshlrev_b32_e32 v16, 2, v28
	v_lshl_add_u64 v[8:9], v[0:1], 0, v[16:17]
	s_mov_b32 s6, 0xd0000
	v_add_co_u32_e32 v10, vcc, s6, v8
	s_mov_b32 s7, 0x1a0000
	s_nop 0
	v_addc_co_u32_e32 v11, vcc, 0, v9, vcc
	global_load_dwordx4 v[0:3], v[8:9], off nt
	global_load_dwordx4 v[4:7], v[10:11], off nt
	v_add_co_u32_e32 v10, vcc, s7, v8
	s_mov_b32 s8, 0x270000
	s_nop 0
	v_addc_co_u32_e32 v11, vcc, 0, v9, vcc
	v_add_co_u32_e32 v8, vcc, s8, v8
	s_movk_i32 s9, 0x204
	s_nop 0
	v_addc_co_u32_e32 v9, vcc, 0, v9, vcc
	global_load_dwordx4 v[12:15], v[10:11], off nt
	s_nop 0
	global_load_dwordx4 v[8:11], v[8:9], off nt
	v_mad_u32_u24 v23, v22, s9, v16
	v_lshlrev_b32_e32 v16, 3, v164
	v_and_b32_e32 v20, 56, v16
	v_lshlrev_b32_e32 v16, 1, v20
	v_lshrrev_b32_e32 v24, 3, v164
	v_lshl_add_u64 v[18:19], s[56:57], 0, v[16:17]
	v_lshlrev_b32_e32 v16, 2, v24
	v_mad_u32_u24 v25, v20, s9, v16
	v_add_u32_e32 v16, 0x200, v164
	v_lshrrev_b32_e32 v26, 3, v16
	v_lshlrev_b32_e32 v16, 2, v26
	s_mov_b64 s[4:5], 0x4000000
	v_mad_u32_u24 v27, v20, s9, v16
	v_lshl_add_u64 v[18:19], v[18:19], 0, s[4:5]
	s_lshl_b32 s9, s2, 7
	s_lshl_b32 s10, s14, 7
	v_mov_b64_e32 v[20:21], s[42:43]
	v_lshlrev_b32_e32 v16, 2, v28
	v_add_u32_e32 v28, 0x2040, v23
	v_add_u32_e32 v29, 0x2048, v23
	v_add_u32_e32 v30, 0x4080, v23
	v_add_u32_e32 v31, 0x4088, v23
	v_add_u32_e32 v32, 0x60c0, v23
	v_add_u32_e32 v33, 0x60c8, v23
	v_add_u32_e32 v34, 0x400, v25
	v_add_u32_e32 v35, 0x800, v25
	v_add_u32_e32 v36, 0xc00, v25
	v_add_u32_e32 v37, 0x400, v27
	v_add_u32_e32 v38, 0x800, v27
	v_add_u32_e32 v39, 0xc00, v27
	s_mov_b32 s11, s2
.LBB0_104:
	s_add_i32 s15, s11, s14
	s_cmpk_lt_i32 s15, 0x1a00
	s_cselect_b64 s[4:5], -1, 0
	s_and_b64 vcc, s[4:5], exec
	s_cselect_b32 s4, s15, s11
	s_mul_hi_i32 s5, s4, 0x4ec4ec4f
	s_lshr_b32 s33, s5, 31
	s_ashr_i32 s5, s5, 5
	s_add_i32 s5, s5, s33
	s_mul_i32 s33, s5, 0x68
	v_lshl_or_b32 v40, s5, 6, v22
	s_sub_i32 s33, s4, s33
	v_mad_i64_i32 v[40:41], s[4:5], v40, s3, v[20:21]
	s_lshl_b32 s4, s33, 7
	s_ashr_i32 s5, s4, 31
	v_lshl_add_u64 v[40:41], s[4:5], 2, v[40:41]
	v_lshl_add_u64 v[44:45], v[40:41], 0, v[16:17]
	v_add_co_u32_e64 v52, s[4:5], s6, v44
	global_load_dwordx4 v[40:43], v[44:45], off nt
	s_nop 0
	v_addc_co_u32_e64 v53, s[4:5], 0, v45, s[4:5]
	v_add_co_u32_e64 v48, s[4:5], s7, v44
	s_nop 1
	v_addc_co_u32_e64 v49, s[4:5], 0, v45, s[4:5]
	v_add_co_u32_e64 v44, s[4:5], s8, v44
	s_nop 1
	v_addc_co_u32_e64 v45, s[4:5], 0, v45, s[4:5]
	global_load_dwordx4 v[44:47], v[44:45], off nt
	s_nop 0
	global_load_dwordx4 v[48:51], v[48:49], off nt
	s_nop 0
	global_load_dwordx4 v[52:55], v[52:53], off nt
	s_mul_hi_i32 s4, s11, 0x4ec4ec4f
	s_lshr_b32 s5, s4, 31
	s_ashr_i32 s4, s4, 5
	s_add_i32 s5, s4, s5
	s_mov_b32 s11, s15
	s_mul_i32 s15, s5, 0xffffcc00
	s_add_i32 s15, s15, s9
	s_waitcnt vmcnt(7)
	ds_write2_b32 v23, v0, v1 offset1:1
	ds_write2_b32 v23, v2, v3 offset0:2 offset1:3
	s_waitcnt vmcnt(6)
	ds_write2_b32 v28, v4, v5 offset1:1
	ds_write2_b32 v29, v6, v7 offset1:1
	s_waitcnt vmcnt(5)
	ds_write2_b32 v30, v12, v13 offset1:1
	ds_write2_b32 v31, v14, v15 offset1:1
	s_waitcnt vmcnt(4)
	ds_write2_b32 v32, v8, v9 offset1:1
	ds_write2_b32 v33, v10, v11 offset1:1
	s_lshl_b32 s4, s5, 6
	v_add_u32_e32 v2, s15, v24
	v_add_u32_e32 v4, s15, v26
	s_ashr_i32 s5, s4, 31
	v_ashrrev_i32_e32 v3, 31, v2
	v_ashrrev_i32_e32 v5, 31, v4
	v_lshl_add_u64 v[0:1], s[4:5], 1, v[18:19]
	v_lshlrev_b64 v[2:3], 13, v[2:3]
	v_lshlrev_b64 v[4:5], 13, v[4:5]
	s_waitcnt lgkmcnt(0)
	s_barrier
	v_lshl_add_u64 v[8:9], v[0:1], 0, v[2:3]
	v_lshl_add_u64 v[10:11], v[0:1], 0, v[4:5]
	ds_read2_b32 v[0:1], v25 offset1:129
	ds_read2_b32 v[2:3], v34 offset0:2 offset1:131
	ds_read2_b32 v[4:5], v35 offset0:4 offset1:133
	ds_read2_b32 v[6:7], v36 offset0:6 offset1:135
	ds_read2_b32 v[12:13], v27 offset1:129
	ds_read2_b32 v[14:15], v37 offset0:2 offset1:131
	ds_read2_b32 v[56:57], v38 offset0:4 offset1:133
	ds_read2_b32 v[58:59], v39 offset0:6 offset1:135
	s_waitcnt lgkmcnt(7)
	v_cvt_pk_bf16_f32 v0, v0, v1
	s_waitcnt lgkmcnt(6)
	v_cvt_pk_bf16_f32 v1, v2, v3
	s_waitcnt lgkmcnt(5)
	v_cvt_pk_bf16_f32 v2, v4, v5
	s_waitcnt lgkmcnt(4)
	v_cvt_pk_bf16_f32 v3, v6, v7
	s_waitcnt lgkmcnt(3)
	v_cvt_pk_bf16_f32 v4, v12, v13
	s_waitcnt lgkmcnt(2)
	v_cvt_pk_bf16_f32 v5, v14, v15
	s_waitcnt lgkmcnt(1)
	v_cvt_pk_bf16_f32 v6, v56, v57
	s_waitcnt lgkmcnt(0)
	v_cvt_pk_bf16_f32 v7, v58, v59
	global_store_dwordx4 v[8:9], v[0:3], off
	global_store_dwordx4 v[10:11], v[4:7], off
	s_waitcnt lgkmcnt(0)
	s_barrier
	s_add_i32 s9, s9, s10
	s_waitcnt vmcnt(5)
	v_mov_b64_e32 v[0:1], v[40:41]
	v_mov_b64_e32 v[2:3], v[42:43]
	s_waitcnt vmcnt(4)
	v_mov_b64_e32 v[8:9], v[44:45]
	s_waitcnt vmcnt(3)
	v_mov_b64_e32 v[12:13], v[48:49]
	s_waitcnt vmcnt(2)
	v_mov_b64_e32 v[4:5], v[52:53]
	v_mov_b64_e32 v[10:11], v[46:47]
	v_mov_b64_e32 v[14:15], v[50:51]
	v_mov_b64_e32 v[6:7], v[54:55]
	s_cbranch_vccnz .LBB0_104
; DEVI unsigned pack2(float a, float b) { f32v2 v = {a, b}; return __builtin_bit_cast(unsigned, __builtin_convertvector(v, bf16v2)); }
; DEVI void lds_barrier() { asm volatile("s_waitcnt lgkmcnt(0)" ::: "memory"); __builtin_amdgcn_s_barrier(); asm volatile("" ::: "memory"); }
; DEVI void tconv_store(const TcPre& R, u16* __restrict__ Wt, int K, int N, int t, float* lds, bool perm) {
;   const int tid = threadIdx.x;
;   const int tnN = N / 128;
;   int tk = t / tnN, tn = t % tnN, k0 = tk * 64, n0 = tn * 128;
;   {
;     float* d = lds + (tid >> 5) * 129 + (tid & 31) * 4;
;     d[0] = R.a[0]; d[1] = R.a[1]; d[2] = R.a[2]; d[3] = R.a[3];
;     d[16 * 129] = R.b[0]; d[16 * 129 + 1] = R.b[1]; d[16 * 129 + 2] = R.b[2]; d[16 * 129 + 3] = R.b[3];
;     d[32 * 129] = R.c[0]; d[32 * 129 + 1] = R.c[1]; d[32 * 129 + 2] = R.c[2]; d[32 * 129 + 3] = R.c[3];
;     d[48 * 129] = R.d[0]; d[48 * 129 + 1] = R.d[1]; d[48 * 129 + 2] = R.d[2]; d[48 * 129 + 3] = R.d[3];
;   }
;   lds_barrier();
;   int n0p = !perm ? n0 : (n0 < DFF ? (n0 / 128) * 256 : ((n0 - DFF) / 128) * 256 + 128);
; #pragma unroll
;   for (int p = 0; p < 2; ++p) {
;     int item = p * 512 + tid, n = item >> 3, kg = item & 7;
;     const float* s = lds + (kg * 8) * 129 + n;
;     uint4 o;
;     o.x = pack2(s[0], s[129]); o.y = pack2(s[2 * 129], s[3 * 129]);
;     o.z = pack2(s[4 * 129], s[5 * 129]); o.w = pack2(s[6 * 129], s[7 * 129]);
;     *(uint4*)(Wt + (size_t)(n0p + n) * K + k0 + kg * 8) = o;
;   }
;   lds_barrier();
; }
; DEVI void tconv(const float* __restrict__ W, u16* __restrict__ Wt, int K, int N, float* lds) {
;   const int ntile = (K / 64) * (N / 128);
;   TcPre R;
;   int t = blockIdx.x;
;   if (t < ntile) tconv_load(W, N, t, R);
;   for (; t < ntile; t += gridDim.x) {
;     TcPre C = R;
;     int nx = t + (int)gridDim.x;
;     tconv_load(W, N, nx < ntile ? nx : t, R);
;     tconv_store(C, Wt, K, N, t, lds, false);
;   }
; }
.LBB0_105:
	s_cmpk_gt_i32 s2, 0x3ff
	s_cbranch_scc1 .LBB0_108
	s_ashr_i32 s3, s2, 31
	s_lshr_b32 s3, s3, 28
	s_add_i32 s3, s2, s3
	s_and_b32 s4, s3, 0x1fffff0
	s_lshl_b32 s3, s3, 2
	s_andn2_b32 s3, s3, 63
	v_lshrrev_b32_e32 v20, 5, v164
	v_or_b32_e32 v0, s3, v20
	s_sub_i32 s4, s2, s4
	v_ashrrev_i32_e32 v1, 31, v0
	s_lshl_b32 s4, s4, 7
	v_lshlrev_b64 v[0:1], 13, v[0:1]
	v_lshlrev_b32_e32 v2, 2, v164
	v_lshl_add_u64 v[0:1], s[44:45], 0, v[0:1]
	s_ashr_i32 s5, s4, 31
	v_and_b32_e32 v26, 0x7c, v2
	v_lshl_add_u64 v[0:1], s[4:5], 2, v[0:1]
	v_mov_b32_e32 v17, 0
	v_lshlrev_b32_e32 v16, 2, v26
	v_lshl_add_u64 v[8:9], v[0:1], 0, v[16:17]
	s_mov_b32 s3, 0x20000
	v_add_co_u32_e32 v10, vcc, s3, v8
	s_mov_b32 s4, 0x40000
	s_nop 0
	v_addc_co_u32_e32 v11, vcc, 0, v9, vcc
	v_add_co_u32_e32 v18, vcc, s4, v8
	s_mov_b32 s5, 0x60000
	s_nop 0
	v_addc_co_u32_e32 v19, vcc, 0, v9, vcc
	v_add_co_u32_e32 v22, vcc, s5, v8
	global_load_dwordx4 v[0:3], v[8:9], off nt
	global_load_dwordx4 v[4:7], v[10:11], off nt
	v_addc_co_u32_e32 v23, vcc, 0, v9, vcc
	global_load_dwordx4 v[12:15], v[18:19], off nt
	global_load_dwordx4 v[8:11], v[22:23], off nt
	s_movk_i32 s8, 0x204
	v_mad_u32_u24 v21, v20, s8, v16
	v_lshlrev_b32_e32 v16, 3, v164
	v_and_b32_e32 v25, 56, v16
	v_lshlrev_b32_e32 v16, 1, v25
	v_lshrrev_b32_e32 v22, 3, v164
	v_lshl_add_u64 v[18:19], s[56:57], 0, v[16:17]
	v_lshlrev_b32_e32 v16, 2, v22
	v_mad_u32_u24 v23, v25, s8, v16
	v_add_u32_e32 v16, 0x200, v164
	v_lshrrev_b32_e32 v24, 3, v16
	v_lshlrev_b32_e32 v16, 2, v24
	s_mov_b64 s[6:7], 0x1ca00000
	v_mad_u32_u24 v25, v25, s8, v16
	v_lshl_add_u64 v[18:19], v[18:19], 0, s[6:7]
	s_lshl_b32 s6, s2, 7
	s_lshl_b32 s7, s14, 7
	v_lshlrev_b32_e32 v16, 2, v26
	v_add_u32_e32 v26, 0x2040, v21
	v_add_u32_e32 v27, 0x2048, v21
	v_add_u32_e32 v28, 0x4080, v21
	v_add_u32_e32 v29, 0x4088, v21
	v_add_u32_e32 v30, 0x60c0, v21
	v_add_u32_e32 v31, 0x60c8, v21
	v_add_u32_e32 v32, 0x400, v23
	v_add_u32_e32 v33, 0x800, v23
	v_add_u32_e32 v34, 0xc00, v23
	v_add_u32_e32 v35, 0x400, v25
	v_add_u32_e32 v36, 0x800, v25
	v_add_u32_e32 v37, 0xc00, v25
	s_mov_b32 s8, s2
.LBB0_107:
	s_add_i32 s9, s8, s14
	s_cmpk_lt_i32 s9, 0x400
	s_cselect_b32 s10, s9, s8
	s_ashr_i32 s11, s10, 31
	s_lshr_b32 s11, s11, 28
	s_add_i32 s11, s10, s11
	s_and_b32 s15, s11, 0x1fffff0
	s_lshl_b32 s11, s11, 2
	s_andn2_b32 s11, s11, 63
	v_or_b32_e32 v38, s11, v20
	s_sub_i32 s10, s10, s15
	v_ashrrev_i32_e32 v39, 31, v38
	s_lshl_b32 s10, s10, 7
	v_lshlrev_b64 v[38:39], 13, v[38:39]
	s_ashr_i32 s11, s10, 31
	v_lshl_add_u64 v[38:39], s[44:45], 0, v[38:39]
	v_lshl_add_u64 v[38:39], s[10:11], 2, v[38:39]
	v_lshl_add_u64 v[42:43], v[38:39], 0, v[16:17]
	v_add_co_u32_e32 v54, vcc, s3, v42
	global_load_dwordx4 v[38:41], v[42:43], off nt
	s_nop 0
	v_addc_co_u32_e32 v55, vcc, 0, v43, vcc
	v_add_co_u32_e32 v56, vcc, s4, v42
	s_ashr_i32 s10, s8, 31
	s_nop 0
	v_addc_co_u32_e32 v57, vcc, 0, v43, vcc
	v_add_co_u32_e32 v42, vcc, s5, v42
	s_lshr_b32 s10, s10, 28
	s_nop 0
	v_addc_co_u32_e32 v43, vcc, 0, v43, vcc
	global_load_dwordx4 v[42:45], v[42:43], off nt
	s_nop 0
	global_load_dwordx4 v[46:49], v[56:57], off nt
	global_load_dwordx4 v[50:53], v[54:55], off nt
	s_add_i32 s10, s8, s10
	s_ashr_i32 s11, s10, 4
	s_lshl_b32 s15, s11, 11
	s_sub_i32 s15, s6, s15
	s_waitcnt vmcnt(7)
	ds_write2_b32 v21, v0, v1 offset1:1
	ds_write2_b32 v21, v2, v3 offset0:2 offset1:3
	s_waitcnt vmcnt(6)
	ds_write2_b32 v26, v4, v5 offset1:1
	ds_write2_b32 v27, v6, v7 offset1:1
	s_waitcnt vmcnt(5)
	ds_write2_b32 v28, v12, v13 offset1:1
	ds_write2_b32 v29, v14, v15 offset1:1
	s_waitcnt vmcnt(4)
	ds_write2_b32 v30, v8, v9 offset1:1
	ds_write2_b32 v31, v10, v11 offset1:1
	s_lshl_b32 s10, s11, 6
	v_add_u32_e32 v2, s15, v22
	v_add_u32_e32 v4, s15, v24
	s_ashr_i32 s11, s10, 31
	v_ashrrev_i32_e32 v3, 31, v2
	v_ashrrev_i32_e32 v5, 31, v4
	v_lshl_add_u64 v[0:1], s[10:11], 1, v[18:19]
	v_lshlrev_b64 v[2:3], 13, v[2:3]
	v_lshlrev_b64 v[4:5], 13, v[4:5]
	s_waitcnt lgkmcnt(0)
	s_barrier
	v_lshl_add_u64 v[8:9], v[0:1], 0, v[2:3]
	v_lshl_add_u64 v[10:11], v[0:1], 0, v[4:5]
	ds_read2_b32 v[0:1], v23 offset1:129
	ds_read2_b32 v[2:3], v32 offset0:2 offset1:131
	ds_read2_b32 v[4:5], v33 offset0:4 offset1:133
	ds_read2_b32 v[6:7], v34 offset0:6 offset1:135
	ds_read2_b32 v[12:13], v25 offset1:129
	ds_read2_b32 v[14:15], v35 offset0:2 offset1:131
	ds_read2_b32 v[54:55], v36 offset0:4 offset1:133
	ds_read2_b32 v[56:57], v37 offset0:6 offset1:135
	s_waitcnt lgkmcnt(7)
	v_cvt_pk_bf16_f32 v0, v0, v1
	s_waitcnt lgkmcnt(6)
	v_cvt_pk_bf16_f32 v1, v2, v3
	s_waitcnt lgkmcnt(5)
	v_cvt_pk_bf16_f32 v2, v4, v5
	s_waitcnt lgkmcnt(4)
	v_cvt_pk_bf16_f32 v3, v6, v7
	s_waitcnt lgkmcnt(3)
	v_cvt_pk_bf16_f32 v4, v12, v13
	s_waitcnt lgkmcnt(2)
	v_cvt_pk_bf16_f32 v5, v14, v15
	s_waitcnt lgkmcnt(1)
	v_cvt_pk_bf16_f32 v6, v54, v55
	s_waitcnt lgkmcnt(0)
	v_cvt_pk_bf16_f32 v7, v56, v57
	global_store_dwordx4 v[8:9], v[0:3], off
	global_store_dwordx4 v[10:11], v[4:7], off
	s_waitcnt lgkmcnt(0)
	s_barrier
	s_add_i32 s6, s6, s7
	s_mov_b32 s8, s9
	s_cmpk_gt_i32 s9, 0x3ff
	s_waitcnt vmcnt(5)
	v_mov_b64_e32 v[0:1], v[38:39]
	v_mov_b64_e32 v[2:3], v[40:41]
	s_waitcnt vmcnt(4)
	v_mov_b64_e32 v[8:9], v[42:43]
	s_waitcnt vmcnt(3)
	v_mov_b64_e32 v[12:13], v[46:47]
	s_waitcnt vmcnt(2)
	v_mov_b64_e32 v[4:5], v[50:51]
	v_mov_b64_e32 v[10:11], v[44:45]
	v_mov_b64_e32 v[14:15], v[48:49]
	v_mov_b64_e32 v[6:7], v[52:53]
	s_cbranch_scc0 .LBB0_107

; template <int MODE> ...
;     ...
;           const long gb = (long)(brow + ai * HALF) * ldc + bcol;
; #pragma unroll 8
;           for (int it = 0; it < 16; ++it) {
;             int item = it * 512 + t2, row = item >> 6, q = item & 63;
;             float4 v = *(const float4*)(ls + row * 1024 + ((q ^ (((row >> 2) & 3) << 3)) << 4));
;             long g = gb + (long)row * ldc + q * 4;
;             float4 r = *(const float4*)(resid + g);
;             if (MODE == 4) {
;               float2 st = *(const float2*)(aux0 + 2 * (long)(brow + ai * HALF + row));
;               float4 gg = *(const float4*)(aux1 + bcol + q * 4), bb = *(const float4*)(aux2 + bcol + q * 4);
;               r.x = (r.x - st.x) * st.y * gg.x + bb.x; r.y = (r.y - st.x) * st.y * gg.y + bb.y;
;               r.z = (r.z - st.x) * st.y * gg.z + bb.z; r.w = (r.w - st.x) * st.y * gg.w + bb.w;
;             }
;             float4 o; o.x = ALPHA * r.x + v.x; o.y = ALPHA * r.y + v.y; o.z = ALPHA * r.z + v.z; o.w = ALPHA * r.w + v.w;
;             *(float4*)(outf + g) = o;
;           }
.LBB0_490:
	v_add_u32_e32 v65, s63, v138
	v_ashrrev_i32_e32 v64, 6, v65
	v_add_u32_e32 v67, 0x200, v65
	v_add_u32_e32 v68, 0x400, v65
	v_add_u32_e32 v87, 0x600, v65
	v_add_u32_e32 v69, 0x800, v65
	v_add_u32_e32 v108, 0xa00, v65
	v_add_u32_e32 v70, 0xc00, v65
	v_add_u32_e32 v109, 0xe00, v65
	v_ashrrev_i32_e32 v65, 31, v64
	v_ashrrev_i32_e32 v142, 6, v67
	v_ashrrev_i32_e32 v116, 6, v68
	v_ashrrev_i32_e32 v162, 6, v87
	v_ashrrev_i32_e32 v118, 6, v69
	v_ashrrev_i32_e32 v170, 6, v108
	v_ashrrev_i32_e32 v124, 6, v70
	v_ashrrev_i32_e32 v172, 6, v109
	v_lshl_add_u64 v[68:69], v[64:65], 0, s[66:67]
	v_ashrrev_i32_e32 v143, 31, v142
	v_ashrrev_i32_e32 v117, 31, v116
	v_ashrrev_i32_e32 v163, 31, v162
	v_ashrrev_i32_e32 v119, 31, v118
	v_ashrrev_i32_e32 v171, 31, v170
	v_ashrrev_i32_e32 v125, 31, v124
	v_ashrrev_i32_e32 v173, 31, v172
	v_lshlrev_b64 v[68:69], 12, v[68:69]
	v_lshl_add_u64 v[70:71], v[142:143], 0, s[66:67]
	v_lshl_add_u64 v[72:73], v[116:117], 0, s[66:67]
	v_lshl_add_u64 v[74:75], v[162:163], 0, s[66:67]
	v_lshl_add_u64 v[76:77], v[118:119], 0, s[66:67]
	v_lshl_add_u64 v[78:79], v[170:171], 0, s[66:67]
	v_lshl_add_u64 v[80:81], v[124:125], 0, s[66:67]
	v_lshl_add_u64 v[82:83], v[172:173], 0, s[66:67]
	v_lshl_add_u64 v[68:69], v[68:69], 0, v[136:137]
	v_lshlrev_b64 v[70:71], 12, v[70:71]
	v_lshlrev_b64 v[72:73], 12, v[72:73]
	v_lshlrev_b64 v[74:75], 12, v[74:75]
	v_lshlrev_b64 v[76:77], 12, v[76:77]
	v_lshlrev_b64 v[78:79], 12, v[78:79]
	v_lshlrev_b64 v[80:81], 12, v[80:81]
	v_lshlrev_b64 v[82:83], 12, v[82:83]
	v_lshlrev_b64 v[186:187], 2, v[68:69]
	v_lshl_add_u64 v[68:69], v[70:71], 0, v[136:137]
	v_lshl_add_u64 v[70:71], v[72:73], 0, v[136:137]
	v_lshl_add_u64 v[72:73], v[74:75], 0, v[136:137]
	v_lshl_add_u64 v[74:75], v[76:77], 0, v[136:137]
	v_lshl_add_u64 v[76:77], v[78:79], 0, v[136:137]
	v_lshl_add_u64 v[78:79], v[80:81], 0, v[136:137]
	v_lshl_add_u64 v[80:81], v[82:83], 0, v[136:137]
	v_lshl_add_u64 v[82:83], s[36:37], 0, v[186:187]
	v_lshlrev_b64 v[188:189], 2, v[68:69]
	v_lshlrev_b64 v[190:191], 2, v[70:71]
	v_lshlrev_b64 v[192:193], 2, v[72:73]
	v_lshlrev_b64 v[194:195], 2, v[74:75]
	v_lshlrev_b64 v[196:197], 2, v[76:77]
	v_lshlrev_b64 v[198:199], 2, v[78:79]
	v_lshlrev_b64 v[200:201], 2, v[80:81]
	global_load_dwordx4 v[68:71], v[82:83], off nt
	v_lshl_add_u64 v[72:73], s[36:37], 0, v[188:189]
	v_lshl_add_u64 v[76:77], s[36:37], 0, v[190:191]
	v_lshl_add_u64 v[80:81], s[36:37], 0, v[192:193]
	v_lshl_add_u64 v[88:89], s[36:37], 0, v[194:195]
	v_lshl_add_u64 v[92:93], s[36:37], 0, v[196:197]
	v_lshl_add_u64 v[96:97], s[36:37], 0, v[198:199]
	v_lshl_add_u64 v[100:101], s[36:37], 0, v[200:201]
	global_load_dwordx4 v[72:75], v[72:73], off nt
	s_nop 0
	global_load_dwordx4 v[76:79], v[76:77], off nt
	s_nop 0
	global_load_dwordx4 v[80:83], v[80:81], off nt
	s_nop 0
	global_load_dwordx4 v[88:91], v[88:89], off nt
	s_nop 0
	global_load_dwordx4 v[92:95], v[92:93], off nt
	s_nop 0
	global_load_dwordx4 v[96:99], v[96:97], off nt
	s_nop 0
	global_load_dwordx4 v[100:103], v[100:101], off nt
	v_lshl_or_b32 v64, v64, 10, v66
	v_lshrrev_b32_e32 v65, 5, v67
	v_lshl_or_b32 v125, v118, 10, v66
	v_lshrrev_b32_e32 v67, 5, v87
	v_lshrrev_b32_e32 v87, 5, v108
	v_lshrrev_b32_e32 v117, 5, v109
	ds_read_b128 v[108:111], v64
	v_lshl_or_b32 v141, v124, 10, v66
	ds_read_b128 v[124:127], v125
	v_bitop3_b32 v64, v65, v139, 24 bitop3:0x6c
	v_lshl_or_b32 v65, v116, 10, v66
	v_bitop3_b32 v67, v67, v139, 24 bitop3:0x6c
	v_bitop3_b32 v87, v87, v139, 24 bitop3:0x6c
	v_bitop3_b32 v143, v117, v139, 24 bitop3:0x6c
	v_lshlrev_b32_e32 v64, 4, v64
	ds_read_b128 v[116:119], v65
	ds_read_b128 v[166:169], v141
	v_lshlrev_b32_e32 v65, 4, v67
	v_lshlrev_b32_e32 v67, 4, v87
	v_lshlrev_b32_e32 v87, 4, v143
	v_lshl_or_b32 v64, v142, 10, v64
	v_lshl_or_b32 v65, v162, 10, v65
	v_lshl_or_b32 v67, v170, 10, v67
	v_lshl_or_b32 v87, v172, 10, v87
	ds_read_b128 v[170:173], v64
	ds_read_b128 v[174:177], v65
	ds_read_b128 v[178:181], v67
	ds_read_b128 v[182:185], v87
	s_addk_i32 s63, 0x1000
	v_lshl_add_u64 v[64:65], s[10:11], 0, v[186:187]
	s_cmpk_eq_i32 s63, 0x2000
	v_lshl_add_u64 v[142:143], s[10:11], 0, v[188:189]
	v_lshl_add_u64 v[162:163], s[10:11], 0, v[190:191]
	v_lshl_add_u64 v[186:187], s[10:11], 0, v[192:193]
	v_lshl_add_u64 v[188:189], s[10:11], 0, v[194:195]
	v_lshl_add_u64 v[190:191], s[10:11], 0, v[196:197]
	v_lshl_add_u64 v[192:193], s[10:11], 0, v[198:199]
	v_lshl_add_u64 v[194:195], s[10:11], 0, v[200:201]
	s_waitcnt vmcnt(0) lgkmcnt(0)
	v_pk_fma_f32 v[68:69], v[68:69], s[62:63], v[108:109] op_sel_hi:[1,0,1]
	v_pk_fma_f32 v[70:71], v[70:71], s[62:63], v[110:111] op_sel_hi:[1,0,1]
	global_store_dwordx4 v[64:65], v[68:71], off
	s_nop 1
	v_pk_fma_f32 v[68:69], v[72:73], s[62:63], v[170:171] op_sel_hi:[1,0,1]
	v_pk_fma_f32 v[70:71], v[74:75], s[62:63], v[172:173] op_sel_hi:[1,0,1]
	v_pk_fma_f32 v[72:73], v[76:77], s[62:63], v[116:117] op_sel_hi:[1,0,1]
	v_pk_fma_f32 v[74:75], v[78:79], s[62:63], v[118:119] op_sel_hi:[1,0,1]
	v_pk_fma_f32 v[76:77], v[80:81], s[62:63], v[174:175] op_sel_hi:[1,0,1]
	v_pk_fma_f32 v[78:79], v[82:83], s[62:63], v[176:177] op_sel_hi:[1,0,1]
	v_pk_fma_f32 v[80:81], v[88:89], s[62:63], v[124:125] op_sel_hi:[1,0,1]
	v_pk_fma_f32 v[82:83], v[90:91], s[62:63], v[126:127] op_sel_hi:[1,0,1]
	v_pk_fma_f32 v[88:89], v[92:93], s[62:63], v[178:179] op_sel_hi:[1,0,1]
	v_pk_fma_f32 v[90:91], v[94:95], s[62:63], v[180:181] op_sel_hi:[1,0,1]
	v_pk_fma_f32 v[92:93], v[96:97], s[62:63], v[166:167] op_sel_hi:[1,0,1]
	v_pk_fma_f32 v[94:95], v[98:99], s[62:63], v[168:169] op_sel_hi:[1,0,1]
	v_pk_fma_f32 v[96:97], v[100:101], s[62:63], v[182:183] op_sel_hi:[1,0,1]
	v_pk_fma_f32 v[98:99], v[102:103], s[62:63], v[184:185] op_sel_hi:[1,0,1]
	global_store_dwordx4 v[142:143], v[68:71], off
	global_store_dwordx4 v[162:163], v[72:75], off
	global_store_dwordx4 v[186:187], v[76:79], off
	global_store_dwordx4 v[188:189], v[80:83], off
	global_store_dwordx4 v[190:191], v[88:91], off
	global_store_dwordx4 v[192:193], v[92:95], off
	global_store_dwordx4 v[194:195], v[96:99], off
	s_cbranch_scc0 .LBB0_490
; DEVI void lds_barrier() { asm volatile("s_waitcnt lgkmcnt(0)" ::: "memory"); __builtin_amdgcn_s_barrier(); asm volatile("" ::: "memory"); }
; template <int MODE> ...
;     ...
;         for (int ai = 0; ai < 2; ++ai) {
;           if (ai) lds_barrier();
; #pragma unroll
;           for (int bj = 0; bj < 2; ++bj)
; #pragma unroll
;             for (int m = 0; m < 4; ++m)
; #pragma unroll
;               for (int n = 0; n < 2; ++n)
; #pragma unroll
;                 for (int j = 0; j < 4; ++j)
;                   *(float*)(ls + wbase + ((m * 16 + j) * 1024 + (bj * 32 + n * 4) * 16)) = acc[ai][bj][m][n][j];
;           lds_barrier();
	s_waitcnt lgkmcnt(0)
	s_barrier
	ds_write2_b32 v140, v0, v32 offset1:16
	ds_write2_b32 v120, v1, v33 offset1:16
	ds_write2_b32 v121, v2, v34 offset1:16
	ds_write2_b32 v122, v3, v35 offset1:16
	ds_write2_b32 v123, v4, v36 offset1:16
	ds_write2_b32 v112, v5, v37 offset1:16
	ds_write2_b32 v113, v6, v38 offset1:16
	ds_write2_b32 v114, v7, v39 offset1:16
	ds_write2_b32 v115, v8, v40 offset1:16
	ds_write2_b32 v104, v9, v41 offset1:16
	ds_write2_b32 v105, v10, v42 offset1:16
	ds_write2_b32 v106, v11, v43 offset1:16
	ds_write2_b32 v107, v12, v44 offset1:16
	ds_write2_b32 v84, v13, v45 offset1:16
	ds_write2_b32 v85, v14, v46 offset1:16
	ds_write2_b32 v86, v15, v47 offset1:16
	ds_write2_b32 v140, v16, v48 offset0:128 offset1:144
	ds_write2_b32 v120, v17, v49 offset0:128 offset1:144
	ds_write2_b32 v121, v18, v50 offset0:128 offset1:144
	ds_write2_b32 v122, v19, v51 offset0:128 offset1:144
	ds_write2_b32 v123, v20, v52 offset0:128 offset1:144
	ds_write2_b32 v112, v21, v53 offset0:128 offset1:144
	ds_write2_b32 v113, v22, v54 offset0:128 offset1:144
	ds_write2_b32 v114, v23, v55 offset0:128 offset1:144
	ds_write2_b32 v115, v24, v56 offset0:128 offset1:144
	ds_write2_b32 v104, v25, v57 offset0:128 offset1:144
	ds_write2_b32 v105, v26, v58 offset0:128 offset1:144
	ds_write2_b32 v106, v27, v59 offset0:128 offset1:144
	ds_write2_b32 v107, v28, v60 offset0:128 offset1:144
	ds_write2_b32 v84, v29, v61 offset0:128 offset1:144
	ds_write2_b32 v85, v30, v62 offset0:128 offset1:144
	ds_write2_b32 v86, v31, v63 offset0:128 offset1:144
	s_waitcnt lgkmcnt(0)
	s_barrier
	s_mov_b32 s63, 0
; DEVI void lds_barrier() { asm volatile("s_waitcnt lgkmcnt(0)" ::: "memory"); __builtin_amdgcn_s_barrier(); asm volatile("" ::: "memory"); }
; template <int MODE> ...
;     ...
;           const long gb = (long)(brow + ai * HALF) * ldc + bcol;
; #pragma unroll 8
;           for (int it = 0; it < 16; ++it) {
;             int item = it * 512 + t2, row = item >> 6, q = item & 63;
;             float4 v = *(const float4*)(ls + row * 1024 + ((q ^ (((row >> 2) & 3) << 3)) << 4));
;             long g = gb + (long)row * ldc + q * 4;
;             float4 r = *(const float4*)(resid + g);
;             if (MODE == 4) {
;               float2 st = *(const float2*)(aux0 + 2 * (long)(brow + ai * HALF + row));
;               float4 gg = *(const float4*)(aux1 + bcol + q * 4), bb = *(const float4*)(aux2 + bcol + q * 4);
;               r.x = (r.x - st.x) * st.y * gg.x + bb.x; r.y = (r.y - st.x) * st.y * gg.y + bb.y;
;               r.z = (r.z - st.x) * st.y * gg.z + bb.z; r.w = (r.w - st.x) * st.y * gg.w + bb.w;
;             }
;             float4 o; o.x = ALPHA * r.x + v.x; o.y = ALPHA * r.y + v.y; o.z = ALPHA * r.z + v.z; o.w = ALPHA * r.w + v.w;
;             *(float4*)(outf + g) = o;
;           }
;         }
;       }
;     }
;     lds_barrier();
;   }
.LBB0_492:
	v_add_u32_e32 v1, s63, v138
	v_ashrrev_i32_e32 v0, 6, v1
	v_add_u32_e32 v34, 0x200, v1
	v_add_u32_e32 v2, 0x400, v1
	v_add_u32_e32 v35, 0x600, v1
	v_add_u32_e32 v3, 0x800, v1
	v_add_u32_e32 v36, 0xa00, v1
	v_add_u32_e32 v4, 0xc00, v1
	v_add_u32_e32 v37, 0xe00, v1
	v_ashrrev_i32_e32 v1, 31, v0
	v_ashrrev_i32_e32 v50, 6, v34
	v_ashrrev_i32_e32 v38, 6, v2
	v_ashrrev_i32_e32 v52, 6, v35
	v_ashrrev_i32_e32 v40, 6, v3
	v_ashrrev_i32_e32 v54, 6, v36
	v_ashrrev_i32_e32 v42, 6, v4
	v_ashrrev_i32_e32 v56, 6, v37
	v_lshl_add_u64 v[2:3], v[0:1], 0, s[64:65]
	v_ashrrev_i32_e32 v51, 31, v50
	v_ashrrev_i32_e32 v39, 31, v38
	v_ashrrev_i32_e32 v53, 31, v52
	v_ashrrev_i32_e32 v41, 31, v40
	v_ashrrev_i32_e32 v55, 31, v54
	v_ashrrev_i32_e32 v43, 31, v42
	v_ashrrev_i32_e32 v57, 31, v56
	v_lshlrev_b64 v[2:3], 12, v[2:3]
	v_lshl_add_u64 v[4:5], v[50:51], 0, s[64:65]
	v_lshl_add_u64 v[6:7], v[38:39], 0, s[64:65]
	v_lshl_add_u64 v[8:9], v[52:53], 0, s[64:65]
	v_lshl_add_u64 v[10:11], v[40:41], 0, s[64:65]
	v_lshl_add_u64 v[12:13], v[54:55], 0, s[64:65]
	v_lshl_add_u64 v[14:15], v[42:43], 0, s[64:65]
	v_lshl_add_u64 v[16:17], v[56:57], 0, s[64:65]
	v_lshl_add_u64 v[2:3], v[2:3], 0, v[136:137]
	v_lshlrev_b64 v[4:5], 12, v[4:5]
	v_lshlrev_b64 v[6:7], 12, v[6:7]
	v_lshlrev_b64 v[8:9], 12, v[8:9]
	v_lshlrev_b64 v[10:11], 12, v[10:11]
	v_lshlrev_b64 v[12:13], 12, v[12:13]
	v_lshlrev_b64 v[14:15], 12, v[14:15]
	v_lshlrev_b64 v[16:17], 12, v[16:17]
	v_lshlrev_b64 v[68:69], 2, v[2:3]
	v_lshl_add_u64 v[2:3], v[4:5], 0, v[136:137]
	v_lshl_add_u64 v[4:5], v[6:7], 0, v[136:137]
	v_lshl_add_u64 v[6:7], v[8:9], 0, v[136:137]
	v_lshl_add_u64 v[8:9], v[10:11], 0, v[136:137]
	v_lshl_add_u64 v[10:11], v[12:13], 0, v[136:137]
	v_lshl_add_u64 v[12:13], v[14:15], 0, v[136:137]
	v_lshl_add_u64 v[14:15], v[16:17], 0, v[136:137]
	v_lshl_add_u64 v[16:17], s[36:37], 0, v[68:69]
	v_lshlrev_b64 v[70:71], 2, v[2:3]
	v_lshlrev_b64 v[72:73], 2, v[4:5]
	v_lshlrev_b64 v[74:75], 2, v[6:7]
	v_lshlrev_b64 v[76:77], 2, v[8:9]
	v_lshlrev_b64 v[78:79], 2, v[10:11]
	v_lshlrev_b64 v[80:81], 2, v[12:13]
	v_lshlrev_b64 v[82:83], 2, v[14:15]
	global_load_dwordx4 v[2:5], v[16:17], off nt
	v_lshl_add_u64 v[6:7], s[36:37], 0, v[70:71]
	v_lshl_add_u64 v[10:11], s[36:37], 0, v[72:73]
	v_lshl_add_u64 v[14:15], s[36:37], 0, v[74:75]
	v_lshl_add_u64 v[18:19], s[36:37], 0, v[76:77]
	v_lshl_add_u64 v[22:23], s[36:37], 0, v[78:79]
	v_lshl_add_u64 v[26:27], s[36:37], 0, v[80:81]
	v_lshl_add_u64 v[30:31], s[36:37], 0, v[82:83]
	global_load_dwordx4 v[6:9], v[6:7], off nt
	s_nop 0
	global_load_dwordx4 v[10:13], v[10:11], off nt
	s_nop 0
	global_load_dwordx4 v[14:17], v[14:15], off nt
	s_nop 0
	global_load_dwordx4 v[18:21], v[18:19], off nt
	s_nop 0
	global_load_dwordx4 v[22:25], v[22:23], off nt
	s_nop 0
	global_load_dwordx4 v[26:29], v[26:27], off nt
	s_nop 0
	global_load_dwordx4 v[30:33], v[30:31], off nt
	v_lshrrev_b32_e32 v41, 5, v36
	v_lshl_or_b32 v0, v0, 10, v66
	v_lshrrev_b32_e32 v1, 5, v34
	v_lshrrev_b32_e32 v43, 5, v37
	v_bitop3_b32 v46, v41, v139, 24 bitop3:0x6c
	v_lshl_or_b32 v47, v42, 10, v66
	v_lshrrev_b32_e32 v39, 5, v35
	ds_read_b128 v[34:37], v0
	v_bitop3_b32 v51, v43, v139, 24 bitop3:0x6c
	v_lshlrev_b32_e32 v53, 4, v46
	ds_read_b128 v[46:49], v47
	v_bitop3_b32 v0, v1, v139, 24 bitop3:0x6c
	v_lshl_or_b32 v1, v38, 10, v66
	v_bitop3_b32 v44, v39, v139, 24 bitop3:0x6c
	v_lshlrev_b32_e32 v0, 4, v0
	v_lshlrev_b32_e32 v51, 4, v51
	v_lshl_or_b32 v45, v40, 10, v66
	ds_read_b128 v[38:41], v1
	v_lshlrev_b32_e32 v1, 4, v44
	v_lshl_or_b32 v0, v50, 10, v0
	v_lshl_or_b32 v58, v54, 10, v53
	v_lshl_or_b32 v62, v56, 10, v51
	ds_read_b128 v[42:45], v45
	v_lshl_or_b32 v1, v52, 10, v1
	ds_read_b128 v[50:53], v0
	ds_read_b128 v[54:57], v1
	ds_read_b128 v[58:61], v58
	ds_read_b128 v[62:65], v62
	s_addk_i32 s63, 0x1000
	v_lshl_add_u64 v[68:69], s[10:11], 0, v[68:69]
	s_cmpk_lg_i32 s63, 0x2000
	v_lshl_add_u64 v[70:71], s[10:11], 0, v[70:71]
	v_lshl_add_u64 v[72:73], s[10:11], 0, v[72:73]
	v_lshl_add_u64 v[74:75], s[10:11], 0, v[74:75]
	v_lshl_add_u64 v[76:77], s[10:11], 0, v[76:77]
	v_lshl_add_u64 v[78:79], s[10:11], 0, v[78:79]
	v_lshl_add_u64 v[80:81], s[10:11], 0, v[80:81]
	v_lshl_add_u64 v[82:83], s[10:11], 0, v[82:83]
	s_waitcnt vmcnt(7) lgkmcnt(7)
	v_pk_fma_f32 v[0:1], v[2:3], s[62:63], v[34:35] op_sel_hi:[1,0,1]
	v_pk_fma_f32 v[2:3], v[4:5], s[62:63], v[36:37] op_sel_hi:[1,0,1]
	global_store_dwordx4 v[68:69], v[0:3], off
	s_waitcnt vmcnt(6) lgkmcnt(5)
	v_pk_fma_f32 v[4:5], v[10:11], s[62:63], v[38:39] op_sel_hi:[1,0,1]
	s_waitcnt vmcnt(5) lgkmcnt(2)
	v_pk_fma_f32 v[10:11], v[16:17], s[62:63], v[56:57] op_sel_hi:[1,0,1]
	v_pk_fma_f32 v[0:1], v[6:7], s[62:63], v[50:51] op_sel_hi:[1,0,1]
	v_pk_fma_f32 v[2:3], v[8:9], s[62:63], v[52:53] op_sel_hi:[1,0,1]
	v_pk_fma_f32 v[6:7], v[12:13], s[62:63], v[40:41] op_sel_hi:[1,0,1]
	v_pk_fma_f32 v[8:9], v[14:15], s[62:63], v[54:55] op_sel_hi:[1,0,1]
	s_waitcnt vmcnt(4)
	v_pk_fma_f32 v[12:13], v[18:19], s[62:63], v[42:43] op_sel_hi:[1,0,1]
	v_pk_fma_f32 v[14:15], v[20:21], s[62:63], v[44:45] op_sel_hi:[1,0,1]
	s_waitcnt vmcnt(3) lgkmcnt(1)
	v_pk_fma_f32 v[16:17], v[22:23], s[62:63], v[58:59] op_sel_hi:[1,0,1]
	v_pk_fma_f32 v[18:19], v[24:25], s[62:63], v[60:61] op_sel_hi:[1,0,1]
	s_waitcnt vmcnt(2)
	v_pk_fma_f32 v[20:21], v[26:27], s[62:63], v[46:47] op_sel_hi:[1,0,1]
	v_pk_fma_f32 v[22:23], v[28:29], s[62:63], v[48:49] op_sel_hi:[1,0,1]
	s_waitcnt vmcnt(1) lgkmcnt(0)
	v_pk_fma_f32 v[24:25], v[30:31], s[62:63], v[62:63] op_sel_hi:[1,0,1]
	v_pk_fma_f32 v[26:27], v[32:33], s[62:63], v[64:65] op_sel_hi:[1,0,1]
	global_store_dwordx4 v[70:71], v[0:3], off
	global_store_dwordx4 v[72:73], v[4:7], off
	global_store_dwordx4 v[74:75], v[8:11], off
	global_store_dwordx4 v[76:77], v[12:15], off
	global_store_dwordx4 v[78:79], v[16:19], off
	global_store_dwordx4 v[80:81], v[20:23], off
	global_store_dwordx4 v[82:83], v[24:27], off
	s_cbranch_scc1 .LBB0_492
	s_waitcnt lgkmcnt(0)
	s_barrier
	s_add_i32 s35, s35, s14
	s_cmpk_gt_i32 s35, 0x1ff
	s_cbranch_scc0 .LBB0_479
